# cross-attention QK blocks: K fragment reads pipelined 8 deep over 8 register quads with counted lgkmcnt waits, chains interleaved (was read-wait-MFMA on one quad); on top of v53
# speedup vs baseline: 1.0005x; 1.0005x over previous
; #define MFMA32(a, b, c) __builtin_amdgcn_mfma_f32_32x32x16_bf16((a), (b), (c), 0, 0, 0)
; DI int crow(int i, int h) { return (i & 3) + 8 * (i >> 2) + 4 * h; }
; DI float fexp2(float x) { return __builtin_amdgcn_exp2f(x); }
; template <int DK, int DV, int MODE, int QB, bool PACK = false>
; DI void attn_item(const AttArgs& a, int q0, int t_lo, int t_hi) {
;     ...
;       for (int qb = 0; qb < QB; ++qb)
; #pragma unroll
;         for (int kb = 0; kb < 2; ++kb) {
; #pragma unroll
;           for (int i = 0; i < 16; ++i) s[qb][kb][i] = 0.f;
;           const unsigned char* kp = Kb + (kb * 32 + r) * KST + h * 16;
; #pragma unroll
;           for (int st = 0; st < NKS; ++st) {
;             const bf16x8 kf = *(const bf16x8*)(kp + st * 32);
;             s[qb][kb] = MFMA32(kf, qf[qb][st], s[qb][kb]);
;           }
;         }
; #pragma unroll
;       for (int qb = 0; qb < QB; ++qb) {
;         const int qidx = wq0 + qb * 32 + r;
;         float mloc = -1e30f;
; #pragma unroll
;         for (int kb = 0; kb < 2; ++kb)
; #pragma unroll
;           for (int i = 0; i < 16; ++i) {
;             float tt = s[qb][kb][i];
;             if constexpr (MODE == 1) {
;               const int kidx = tile * 64 + kb * 32 + crow(i, h);
;               const int d = kidx - qidx;
;               tt = (d <= 128 && d >= -128) ? tt : -1e30f;
;               s[qb][kb][i] = tt;
;             }
;             if constexpr (MODE == 2) {
;               const int kc = kb * 32 + crow(i, h);
;               const bool ok = (kc >= c0[qb]) && (kc < c0[qb] + 16);
;               const int bi = ok ? ((tile - rq + 7) * 31 + kc - cq[qb] + 15) : 0;
;               tt = ok ? fmaf(tt, scale, rpbs[bi]) : -1e30f;
;               s[qb][kb][i] = tt;
;             }
;             mloc = fmaxf(mloc, tt);
;           }
;         mloc = fmaxf(mloc, __shfl_xor(mloc, 32));
;         if (__any((mloc - m[qb]) * cexp > 8.f)) {
;           const float mnew = fmaxf(m[qb], mloc);
;           const float alpha = fexp2((m[qb] - mnew) * cexp);
;           m[qb] = mnew;
;           lsum[qb] *= alpha;
; #pragma unroll
;           for (int d = 0; d < NDB; ++d)
; #pragma unroll
;             for (int i = 0; i < 16; ++i) o[qb][d][i] *= alpha;
;         }
.LBB0_1093:
	s_mul_i32 s12, s21, 0x8800
	v_or_b32_e32 v0, s12, v162
	v_add_u32_e32 v0, v0, v167
	ds_read_b128 v[4:7], v0
	ds_read_b128 v[8:11], v0 offset:8704
	ds_read_b128 v[176:179], v0 offset:32
	ds_read_b128 v[180:183], v0 offset:8736
	ds_read_b128 v[184:187], v0 offset:64
	ds_read_b128 v[188:191], v0 offset:8768
	ds_read_b128 v[192:195], v0 offset:96
	ds_read_b128 v[196:199], v0 offset:8800
	s_waitcnt lgkmcnt(7)
	v_mfma_f32_32x32x16_bf16 v[80:95], v[4:7], v[140:143], 0
	ds_read_b128 v[4:7], v0 offset:128
	s_waitcnt lgkmcnt(7)
	v_mfma_f32_32x32x16_bf16 v[96:111], v[8:11], v[140:143], 0
	ds_read_b128 v[8:11], v0 offset:8832
	s_waitcnt lgkmcnt(7)
	v_mfma_f32_32x32x16_bf16 v[80:95], v[176:179], v[136:139], v[80:95]
	ds_read_b128 v[176:179], v0 offset:160
	s_waitcnt lgkmcnt(7)
	v_mfma_f32_32x32x16_bf16 v[96:111], v[180:183], v[136:139], v[96:111]
	ds_read_b128 v[180:183], v0 offset:8864
	s_waitcnt lgkmcnt(7)
	v_mfma_f32_32x32x16_bf16 v[80:95], v[184:187], v[132:135], v[80:95]
	ds_read_b128 v[184:187], v0 offset:192
	s_waitcnt lgkmcnt(7)
	v_mfma_f32_32x32x16_bf16 v[96:111], v[188:191], v[132:135], v[96:111]
	ds_read_b128 v[188:191], v0 offset:8896
	s_waitcnt lgkmcnt(7)
	v_mfma_f32_32x32x16_bf16 v[80:95], v[192:195], v[128:131], v[80:95]
	ds_read_b128 v[192:195], v0 offset:224
	s_waitcnt lgkmcnt(7)
	v_mfma_f32_32x32x16_bf16 v[96:111], v[196:199], v[128:131], v[96:111]
	ds_read_b128 v[196:199], v0 offset:8928
	s_waitcnt lgkmcnt(7)
	v_mfma_f32_32x32x16_bf16 v[80:95], v[4:7], v[124:127], v[80:95]
	s_waitcnt lgkmcnt(6)
	v_mfma_f32_32x32x16_bf16 v[96:111], v[8:11], v[124:127], v[96:111]
	s_waitcnt lgkmcnt(5)
	v_mfma_f32_32x32x16_bf16 v[80:95], v[176:179], v[120:123], v[80:95]
	s_waitcnt lgkmcnt(4)
	v_mfma_f32_32x32x16_bf16 v[96:111], v[180:183], v[120:123], v[96:111]
	s_waitcnt lgkmcnt(3)
	v_mfma_f32_32x32x16_bf16 v[80:95], v[184:187], v[116:119], v[80:95]
	s_waitcnt lgkmcnt(2)
	v_mfma_f32_32x32x16_bf16 v[96:111], v[188:191], v[116:119], v[96:111]
	s_waitcnt lgkmcnt(1)
	v_mfma_f32_32x32x16_bf16 v[80:95], v[192:195], v[112:115], v[80:95]
	s_waitcnt lgkmcnt(0)
	v_mfma_f32_32x32x16_bf16 v[96:111], v[196:199], v[112:115], v[96:111]
	s_nop 10
	v_and_b32_e32 v1, 64, v225
	v_add_u32_e32 v1, 64, v1
	s_mov_b32 s13, 0xf149f2ca
	v_xor_b32_e32 v0, 32, v225
	v_cmp_lt_i32_e32 vcc, v0, v1
	v_max3_f32 v1, v80, s13, v81
	v_max3_f32 v1, v1, v82, v83
	v_max3_f32 v1, v1, v84, v85
	v_max3_f32 v1, v1, v86, v87
	v_max3_f32 v1, v1, v88, v89
	v_max3_f32 v1, v1, v90, v91
	v_max3_f32 v1, v1, v92, v93
	v_max3_f32 v1, v1, v94, v95
	v_cndmask_b32_e32 v0, v225, v0, vcc
	v_lshlrev_b32_e32 v3, 2, v0
	s_mov_b32 s13, 0x41000000
	s_nop 4
	v_max3_f32 v1, v1, v96, v97
	v_max3_f32 v1, v1, v98, v99
	v_max3_f32 v1, v1, v100, v101
	v_max3_f32 v1, v1, v102, v103
	v_max3_f32 v1, v1, v104, v105
	v_max3_f32 v1, v1, v106, v107
	v_max3_f32 v1, v1, v108, v109
	v_max3_f32 v1, v1, v110, v111
	ds_bpermute_b32 v0, v3, v1
	s_waitcnt lgkmcnt(0)
	v_max_f32_e32 v0, v0, v0
	v_max_f32_e32 v0, v1, v0
	v_sub_f32_e32 v1, v0, v168
	v_mul_f32_e32 v1, 0x3e0293ee, v1
	v_cmp_lt_f32_e32 vcc, s13, v1
	s_cbranch_vccz .LBB0_1084
	v_max_f32_e32 v0, v0, v0
	v_max_f32_e32 v1, v168, v168
	v_max_f32_e32 v1, v1, v0
	v_sub_f32_e32 v0, v168, v1
	v_mul_f32_e32 v0, 0x3e0293ee, v0
	v_exp_f32_e32 v0, v0
	v_mov_b32_e32 v168, v1
	v_pk_mul_f32 v[78:79], v[78:79], v[0:1] op_sel_hi:[1,0]
	v_pk_mul_f32 v[76:77], v[76:77], v[0:1] op_sel_hi:[1,0]
	v_pk_mul_f32 v[74:75], v[74:75], v[0:1] op_sel_hi:[1,0]
	v_pk_mul_f32 v[72:73], v[72:73], v[0:1] op_sel_hi:[1,0]
	v_pk_mul_f32 v[70:71], v[70:71], v[0:1] op_sel_hi:[1,0]
	v_pk_mul_f32 v[68:69], v[68:69], v[0:1] op_sel_hi:[1,0]
	v_pk_mul_f32 v[66:67], v[66:67], v[0:1] op_sel_hi:[1,0]
	v_pk_mul_f32 v[64:65], v[64:65], v[0:1] op_sel_hi:[1,0]
	v_pk_mul_f32 v[62:63], v[62:63], v[0:1] op_sel_hi:[1,0]
	v_pk_mul_f32 v[60:61], v[60:61], v[0:1] op_sel_hi:[1,0]
	v_pk_mul_f32 v[58:59], v[58:59], v[0:1] op_sel_hi:[1,0]
	v_pk_mul_f32 v[56:57], v[56:57], v[0:1] op_sel_hi:[1,0]
	v_pk_mul_f32 v[54:55], v[54:55], v[0:1] op_sel_hi:[1,0]
	v_pk_mul_f32 v[52:53], v[52:53], v[0:1] op_sel_hi:[1,0]
	v_pk_mul_f32 v[50:51], v[50:51], v[0:1] op_sel_hi:[1,0]
	v_pk_mul_f32 v[48:49], v[48:49], v[0:1] op_sel_hi:[1,0]
	v_pk_mul_f32 v[46:47], v[46:47], v[0:1] op_sel_hi:[1,0]
	v_pk_mul_f32 v[44:45], v[44:45], v[0:1] op_sel_hi:[1,0]
	v_pk_mul_f32 v[42:43], v[42:43], v[0:1] op_sel_hi:[1,0]
	v_pk_mul_f32 v[40:41], v[40:41], v[0:1] op_sel_hi:[1,0]
	v_pk_mul_f32 v[38:39], v[38:39], v[0:1] op_sel_hi:[1,0]
	v_pk_mul_f32 v[36:37], v[36:37], v[0:1] op_sel_hi:[1,0]
	v_pk_mul_f32 v[34:35], v[34:35], v[0:1] op_sel_hi:[1,0]
	v_pk_mul_f32 v[32:33], v[32:33], v[0:1] op_sel_hi:[1,0]
	v_pk_mul_f32 v[30:31], v[30:31], v[0:1] op_sel_hi:[1,0]
	v_pk_mul_f32 v[28:29], v[28:29], v[0:1] op_sel_hi:[1,0]
	v_pk_mul_f32 v[26:27], v[26:27], v[0:1] op_sel_hi:[1,0]
	v_pk_mul_f32 v[24:25], v[24:25], v[0:1] op_sel_hi:[1,0]
	v_pk_mul_f32 v[22:23], v[22:23], v[0:1] op_sel_hi:[1,0]
	v_pk_mul_f32 v[20:21], v[20:21], v[0:1] op_sel_hi:[1,0]
	v_pk_mul_f32 v[18:19], v[18:19], v[0:1] op_sel_hi:[1,0]
	v_pk_mul_f32 v[16:17], v[16:17], v[0:1] op_sel_hi:[1,0]
	v_mul_f32_e32 v164, v164, v0
	s_branch .LBB0_1084
; #define MFMA32(a, b, c) __builtin_amdgcn_mfma_f32_32x32x16_bf16((a), (b), (c), 0, 0, 0)
; DI int crow(int i, int h) { return (i & 3) + 8 * (i >> 2) + 4 * h; }
; DI float fexp2(float x) { return __builtin_amdgcn_exp2f(x); }
; template <int DK, int DV, int MODE, int QB, bool PACK = false>
; DI void attn_item(const AttArgs& a, int q0, int t_lo, int t_hi) {
;     ...
;       for (int qb = 0; qb < QB; ++qb)
; #pragma unroll
;         for (int kb = 0; kb < 2; ++kb) {
; #pragma unroll
;           for (int i = 0; i < 16; ++i) s[qb][kb][i] = 0.f;
;           const unsigned char* kp = Kb + (kb * 32 + r) * KST + h * 16;
; #pragma unroll
;           for (int st = 0; st < NKS; ++st) {
;             const bf16x8 kf = *(const bf16x8*)(kp + st * 32);
;             s[qb][kb] = MFMA32(kf, qf[qb][st], s[qb][kb]);
;           }
;         }
; #pragma unroll
;       for (int qb = 0; qb < QB; ++qb) {
;         const int qidx = wq0 + qb * 32 + r;
;         float mloc = -1e30f;
; #pragma unroll
;         for (int kb = 0; kb < 2; ++kb)
; #pragma unroll
;           for (int i = 0; i < 16; ++i) {
;             float tt = s[qb][kb][i];
;             if constexpr (MODE == 1) {
;               const int kidx = tile * 64 + kb * 32 + crow(i, h);
;               const int d = kidx - qidx;
;               tt = (d <= 128 && d >= -128) ? tt : -1e30f;
;               s[qb][kb][i] = tt;
;             }
;             if constexpr (MODE == 2) {
;               const int kc = kb * 32 + crow(i, h);
;               const bool ok = (kc >= c0[qb]) && (kc < c0[qb] + 16);
;               const int bi = ok ? ((tile - rq + 7) * 31 + kc - cq[qb] + 15) : 0;
;               tt = ok ? fmaf(tt, scale, rpbs[bi]) : -1e30f;
;               s[qb][kb][i] = tt;
;             }
;             mloc = fmaxf(mloc, tt);
;           }
;         mloc = fmaxf(mloc, __shfl_xor(mloc, 32));
;         if (__any((mloc - m[qb]) * cexp > 8.f)) {
;           const float mnew = fmaxf(m[qb], mloc);
;           const float alpha = fexp2((m[qb] - mnew) * cexp);
;           m[qb] = mnew;
;           lsum[qb] *= alpha;
; #pragma unroll
;           for (int d = 0; d < NDB; ++d)
; #pragma unroll
;             for (int i = 0; i < 16; ++i) o[qb][d][i] *= alpha;
;         }
.LBB0_1095:
	v_add_u32_e32 v1, v162, v167
	ds_read_b128 v[4:7], v1 offset:34816
	ds_read_b128 v[8:11], v1 offset:43520
	ds_read_b128 v[176:179], v1 offset:34848
	ds_read_b128 v[180:183], v1 offset:43552
	ds_read_b128 v[184:187], v1 offset:34880
	ds_read_b128 v[188:191], v1 offset:43584
	ds_read_b128 v[192:195], v1 offset:34912
	ds_read_b128 v[196:199], v1 offset:43616
	s_waitcnt lgkmcnt(7)
	v_mfma_f32_32x32x16_bf16 v[80:95], v[4:7], v[140:143], 0
	ds_read_b128 v[4:7], v1 offset:34944
	s_waitcnt lgkmcnt(7)
	v_mfma_f32_32x32x16_bf16 v[96:111], v[8:11], v[140:143], 0
	ds_read_b128 v[8:11], v1 offset:43648
	s_waitcnt lgkmcnt(7)
	v_mfma_f32_32x32x16_bf16 v[80:95], v[176:179], v[136:139], v[80:95]
	ds_read_b128 v[176:179], v1 offset:34976
	s_waitcnt lgkmcnt(7)
	v_mfma_f32_32x32x16_bf16 v[96:111], v[180:183], v[136:139], v[96:111]
	ds_read_b128 v[180:183], v1 offset:43680
	s_waitcnt lgkmcnt(7)
	v_mfma_f32_32x32x16_bf16 v[80:95], v[184:187], v[132:135], v[80:95]
	ds_read_b128 v[184:187], v1 offset:35008
	s_waitcnt lgkmcnt(7)
	v_mfma_f32_32x32x16_bf16 v[96:111], v[188:191], v[132:135], v[96:111]
	ds_read_b128 v[188:191], v1 offset:43712
	s_waitcnt lgkmcnt(7)
	v_mfma_f32_32x32x16_bf16 v[80:95], v[192:195], v[128:131], v[80:95]
	ds_read_b128 v[192:195], v1 offset:35040
	s_waitcnt lgkmcnt(7)
	v_mfma_f32_32x32x16_bf16 v[96:111], v[196:199], v[128:131], v[96:111]
	ds_read_b128 v[196:199], v1 offset:43744
	s_waitcnt lgkmcnt(7)
	v_mfma_f32_32x32x16_bf16 v[80:95], v[4:7], v[124:127], v[80:95]
	s_waitcnt lgkmcnt(6)
	v_mfma_f32_32x32x16_bf16 v[96:111], v[8:11], v[124:127], v[96:111]
	s_waitcnt lgkmcnt(5)
	v_mfma_f32_32x32x16_bf16 v[80:95], v[176:179], v[120:123], v[80:95]
	s_waitcnt lgkmcnt(4)
	v_mfma_f32_32x32x16_bf16 v[96:111], v[180:183], v[120:123], v[96:111]
	s_waitcnt lgkmcnt(3)
	v_mfma_f32_32x32x16_bf16 v[80:95], v[184:187], v[116:119], v[80:95]
	s_waitcnt lgkmcnt(2)
	v_mfma_f32_32x32x16_bf16 v[96:111], v[188:191], v[116:119], v[96:111]
	s_waitcnt lgkmcnt(1)
	v_mfma_f32_32x32x16_bf16 v[80:95], v[192:195], v[112:115], v[80:95]
	s_waitcnt lgkmcnt(0)
	v_mfma_f32_32x32x16_bf16 v[96:111], v[196:199], v[112:115], v[96:111]
	s_nop 10
	s_mov_b32 s2, 0xf149f2ca
	v_max3_f32 v1, v80, s2, v81
	v_max3_f32 v1, v1, v82, v83
	v_max3_f32 v1, v1, v84, v85
	v_max3_f32 v1, v1, v86, v87
	v_max3_f32 v1, v1, v88, v89
	v_max3_f32 v1, v1, v90, v91
	v_max3_f32 v1, v1, v92, v93
	v_max3_f32 v1, v1, v94, v95
	s_mov_b32 s2, 0x41000000
	s_nop 8
	v_max3_f32 v1, v1, v96, v97
	v_max3_f32 v1, v1, v98, v99
	v_max3_f32 v1, v1, v100, v101
	v_max3_f32 v1, v1, v102, v103
	v_max3_f32 v1, v1, v104, v105
	v_max3_f32 v1, v1, v106, v107
	v_max3_f32 v1, v1, v108, v109
	v_max3_f32 v1, v1, v110, v111
	ds_bpermute_b32 v4, v3, v1
	s_waitcnt lgkmcnt(0)
	v_max_f32_e32 v4, v4, v4
	v_max_f32_e32 v1, v1, v4
	v_sub_f32_e32 v4, v1, v168
	v_mul_f32_e32 v4, 0x3e0293ee, v4
	v_cmp_lt_f32_e32 vcc, s2, v4
	s_cbranch_vccz .LBB0_1076
	v_max_f32_e32 v0, v1, v1
	v_max_f32_e32 v1, v168, v168
	v_max_f32_e32 v1, v1, v0
	v_sub_f32_e32 v0, v168, v1
	v_mul_f32_e32 v0, 0x3e0293ee, v0
	v_exp_f32_e32 v0, v0
	s_nop 0
	v_pk_mul_f32 v[78:79], v[78:79], v[0:1] op_sel_hi:[1,0]
	v_pk_mul_f32 v[76:77], v[76:77], v[0:1] op_sel_hi:[1,0]
	v_pk_mul_f32 v[74:75], v[74:75], v[0:1] op_sel_hi:[1,0]
	v_pk_mul_f32 v[72:73], v[72:73], v[0:1] op_sel_hi:[1,0]
	v_pk_mul_f32 v[70:71], v[70:71], v[0:1] op_sel_hi:[1,0]
	v_pk_mul_f32 v[68:69], v[68:69], v[0:1] op_sel_hi:[1,0]
	v_pk_mul_f32 v[66:67], v[66:67], v[0:1] op_sel_hi:[1,0]
	v_pk_mul_f32 v[64:65], v[64:65], v[0:1] op_sel_hi:[1,0]
	v_pk_mul_f32 v[62:63], v[62:63], v[0:1] op_sel_hi:[1,0]
	v_pk_mul_f32 v[60:61], v[60:61], v[0:1] op_sel_hi:[1,0]
	v_pk_mul_f32 v[58:59], v[58:59], v[0:1] op_sel_hi:[1,0]
	v_pk_mul_f32 v[56:57], v[56:57], v[0:1] op_sel_hi:[1,0]
	v_pk_mul_f32 v[54:55], v[54:55], v[0:1] op_sel_hi:[1,0]
	v_pk_mul_f32 v[52:53], v[52:53], v[0:1] op_sel_hi:[1,0]
	v_pk_mul_f32 v[50:51], v[50:51], v[0:1] op_sel_hi:[1,0]
	v_pk_mul_f32 v[48:49], v[48:49], v[0:1] op_sel_hi:[1,0]
	v_pk_mul_f32 v[46:47], v[46:47], v[0:1] op_sel_hi:[1,0]
	v_pk_mul_f32 v[44:45], v[44:45], v[0:1] op_sel_hi:[1,0]
	v_pk_mul_f32 v[42:43], v[42:43], v[0:1] op_sel_hi:[1,0]
	v_pk_mul_f32 v[40:41], v[40:41], v[0:1] op_sel_hi:[1,0]
	v_pk_mul_f32 v[38:39], v[38:39], v[0:1] op_sel_hi:[1,0]
	v_pk_mul_f32 v[36:37], v[36:37], v[0:1] op_sel_hi:[1,0]
	v_pk_mul_f32 v[34:35], v[34:35], v[0:1] op_sel_hi:[1,0]
	v_pk_mul_f32 v[32:33], v[32:33], v[0:1] op_sel_hi:[1,0]
	v_pk_mul_f32 v[30:31], v[30:31], v[0:1] op_sel_hi:[1,0]
	v_pk_mul_f32 v[28:29], v[28:29], v[0:1] op_sel_hi:[1,0]
	v_pk_mul_f32 v[26:27], v[26:27], v[0:1] op_sel_hi:[1,0]
	v_pk_mul_f32 v[24:25], v[24:25], v[0:1] op_sel_hi:[1,0]
	v_pk_mul_f32 v[22:23], v[22:23], v[0:1] op_sel_hi:[1,0]
	v_pk_mul_f32 v[20:21], v[20:21], v[0:1] op_sel_hi:[1,0]
	v_pk_mul_f32 v[18:19], v[18:19], v[0:1] op_sel_hi:[1,0]
	v_pk_mul_f32 v[16:17], v[16:17], v[0:1] op_sel_hi:[1,0]
	v_mul_f32_e32 v164, v164, v0
	v_mul_f32_e32 v0, 0xbe0293ee, v1
	s_branch .LBB0_1076
